# P0 weight-conversion loop: the vmcnt(0) hipcc placed right after the next item's prefetch loads moved behind the convert+store block (prefetch now overlaps the conversion); stacked on pipelined claims
# speedup vs baseline: 1.0046x; 1.0046x over previous
.LBB0_25:
	s_andn2_b64 vcc, exec, s[58:59]
	s_cbranch_vccnz .LBB0_96
	s_mov_b32 s5, 0
	s_movk_i32 s27, 0x2b0
	s_mov_b32 s38, 0x23000000
	s_movk_i32 s39, 0xf9c4
	s_movk_i32 s52, 0xdc0
	s_movk_i32 s53, 0x5600
	s_mov_b32 s56, 0xb002300
	v_mov_b32_e32 v85, 0
	s_mov_b32 s57, 0xc3e00000
	v_mov_b32_e32 v27, 0x46000000
	v_mov_b32_e32 v87, 0x44800000
	v_mov_b32_e32 v88, 0x43e00000
	s_mov_b32 s66, 0
	s_waitcnt vmcnt(0)
	s_branch .LBB0_28
.LBB0_27:
	s_waitcnt vmcnt(0)
	s_andn2_b64 vcc, exec, s[54:55]
	s_mov_b64 s[24:25], s[58:59]
	s_mov_b32 s4, s64
	s_mov_b32 s26, s65
	s_mov_b32 s50, s60
	v_mov_b32_e32 v86, v90
	v_mov_b32_e32 v2, v56
	v_mov_b32_e32 v76, v57
	v_mov_b32_e32 v4, v58
	v_mov_b32_e32 v68, v59
	v_mov_b32_e32 v26, v52
	v_mov_b32_e32 v77, v53
	v_mov_b32_e32 v5, v54
	v_mov_b32_e32 v69, v55
	v_mov_b32_e32 v10, v44
	v_mov_b32_e32 v78, v45
	v_mov_b32_e32 v12, v46
	v_mov_b32_e32 v70, v47
	v_mov_b32_e32 v11, v40
	v_mov_b32_e32 v79, v41
	v_mov_b32_e32 v13, v42
	v_mov_b32_e32 v71, v43
	v_mov_b32_e32 v6, v36
	v_mov_b32_e32 v80, v37
	v_mov_b32_e32 v8, v38
	v_mov_b32_e32 v72, v39
	v_mov_b32_e32 v7, v32
	v_mov_b32_e32 v81, v33
	v_mov_b32_e32 v9, v34
	v_mov_b32_e32 v73, v35
	v_mov_b32_e32 v14, v28
	v_mov_b32_e32 v82, v29
	v_mov_b32_e32 v16, v30
	v_mov_b32_e32 v74, v31
	v_mov_b32_e32 v15, v48
	v_mov_b32_e32 v83, v49
	v_mov_b32_e32 v17, v50
	v_mov_b32_e32 v75, v51
	v_mov_b32_e32 v22, v60
	v_mov_b32_e32 v23, v61
	v_mov_b32_e32 v24, v62
	v_mov_b32_e32 v25, v63
	v_mov_b32_e32 v18, v64
	v_mov_b32_e32 v19, v65
	v_mov_b32_e32 v20, v66
	v_mov_b32_e32 v21, v67
	s_cbranch_vccz .LBB0_96

.LBB0_53:
	v_mov_b32_e32 v63, v89
	v_mov_b32_e32 v62, v89
	v_mov_b32_e32 v61, v89
	v_mov_b32_e32 v60, v89
	v_mov_b32_e32 v67, v89
	v_mov_b32_e32 v66, v89
	v_mov_b32_e32 v65, v89
	v_mov_b32_e32 v64, v89
.LBB0_54:
	v_mul_f32_e32 v91, v2, v22
	v_add_u32_e32 v2, s26, v1
	v_ashrrev_i32_e32 v92, 31, v2
	v_mad_u64_u32 v[2:3], s[36:37], v2, s4, 0
	v_mov_b32_e32 v84, v3
	v_cmp_nlt_f32_e32 vcc, 0, v86
	v_mad_u64_u32 v[92:93], s[36:37], v92, s4, v[84:85]
	v_mov_b32_e32 v3, v92
	s_ashr_i32 s51, s50, 31
	s_mov_b64 s[36:37], -1
	v_mul_f32_e32 v26, v26, v23
	s_cbranch_vccz .LBB0_56
	v_lshl_add_u64 v[92:93], v[2:3], 1, s[24:25]
	v_lshl_add_u64 v[92:93], s[50:51], 1, v[92:93]
	v_lshlrev_b32_e32 v84, 1, v164
	v_pk_mul_f32 v[94:95], v[10:11], v[24:25]
	v_lshl_add_u64 v[96:97], v[92:93], 0, v[84:85]
	v_cvt_pk_bf16_f32 v93, v94, v95
	v_pk_mul_f32 v[94:95], v[6:7], v[18:19]
	v_pk_mul_f32 v[98:99], v[14:15], v[20:21]
	v_cvt_pk_bf16_f32 v92, v91, v26
	v_cvt_pk_bf16_f32 v94, v94, v95
	v_cvt_pk_bf16_f32 v95, v98, v99
	global_store_dwordx4 v[96:97], v[92:95], off
	v_pk_mul_f32 v[98:99], v[82:83], v[20:21]
	s_lshl_b64 s[36:37], s[4:5], 1
	v_pk_mul_f32 v[92:93], v[76:77], v[22:23]
	v_pk_mul_f32 v[94:95], v[78:79], v[24:25]
	v_cvt_pk_bf16_f32 v92, v92, v93
	v_cvt_pk_bf16_f32 v93, v94, v95
	v_pk_mul_f32 v[94:95], v[80:81], v[18:19]
	v_lshl_add_u64 v[96:97], v[96:97], 0, s[36:37]
	v_cvt_pk_bf16_f32 v94, v94, v95
	v_cvt_pk_bf16_f32 v95, v98, v99
	global_store_dwordx4 v[96:97], v[92:95], off
	v_pk_mul_f32 v[98:99], v[16:17], v[20:21]
	v_lshl_add_u64 v[96:97], v[96:97], 0, s[36:37]
	v_pk_mul_f32 v[92:93], v[4:5], v[22:23]
	v_pk_mul_f32 v[94:95], v[12:13], v[24:25]
	v_cvt_pk_bf16_f32 v92, v92, v93
	v_cvt_pk_bf16_f32 v93, v94, v95
	v_pk_mul_f32 v[94:95], v[8:9], v[18:19]
	s_nop 0
	v_cvt_pk_bf16_f32 v94, v94, v95
	v_cvt_pk_bf16_f32 v95, v98, v99
	global_store_dwordx4 v[96:97], v[92:95], off
	v_pk_mul_f32 v[98:99], v[74:75], v[20:21]
	v_lshl_add_u64 v[96:97], v[96:97], 0, s[36:37]
	v_pk_mul_f32 v[92:93], v[68:69], v[22:23]
	v_pk_mul_f32 v[94:95], v[70:71], v[24:25]
	v_cvt_pk_bf16_f32 v92, v92, v93
	v_cvt_pk_bf16_f32 v93, v94, v95
	v_pk_mul_f32 v[94:95], v[72:73], v[18:19]
	s_mov_b64 s[36:37], 0
	v_cvt_pk_bf16_f32 v94, v94, v95
	v_cvt_pk_bf16_f32 v95, v98, v99
	global_store_dwordx4 v[96:97], v[92:95], off
